# speedup vs baseline: 1.0361x; 1.0049x over previous
; __device__ __forceinline__ void softmax_pv(f32x16& s0, f32x16& s1, float& mref, f32x16& negm, float& lsum, f32x16 (&o)[2], LAS float* fac, const bf16x8 (&vf)[2][4], bool first, int r32, int hi) {
;     ...
;     float ps0 = 0.f, ps1 = 0.f;
; #pragma unroll
;     for (int r = 0; r < 16; ++r) { s0[r] = __builtin_amdgcn_exp2f(s0[r]); s1[r] = __builtin_amdgcn_exp2f(s1[r]); ps0 += s0[r]; ps1 += s1[r]; }
;     lsum += ps0 + ps1;
;     bf16x8 pa[4];
; #pragma unroll
;     for (int k = 0; k < 4; ++k) {
;         const f32x16& s = (k < 2) ? s0 : s1; const int rb = 8 * (k & 1);
;         u32x4 w; w.x = cvt_pk_bf16(s[rb + 0], s[rb + 1]); w.y = cvt_pk_bf16(s[rb + 2], s[rb + 3]); w.z = cvt_pk_bf16(s[rb + 4], s[rb + 5]); w.w = cvt_pk_bf16(s[rb + 6], s[rb + 7]);
;         pa[k] = __builtin_bit_cast(bf16x8, w);
;     }
; #pragma unroll
;     for (int k = 0; k < 4; ++k) {
;         o[0] = __builtin_amdgcn_mfma_f32_32x32x16_bf16(pa[k], vf[0][k], o[0], 0, 0, 0);
; template <bool DIFF>
; __device__ __forceinline__ void attn_item(const Params& p, int l, int I, LAS unsigned char* lds, const int tid) {
;     ...
;         const LAS unsigned char* sb = lds + (st & 1) * AT_SLOT + sub * AT_SUB;
;         const LAS unsigned char* kb = sb + hi * 1024 + r32 * 16;
;         const LAS unsigned char* vb = sb + AT_V + vlane;
;         bf16x8 vf[2][4];
; #pragma unroll
;         for (int dh = 0; dh < 2; ++dh)
; #pragma unroll
;             for (int k = 0; k < 4; ++k) { const s16x4 lo = vtr(vb + dh * 4096 + k * 1024), hh = vtr(vb + dh * 4096 + k * 1024 + 512);
;                 vf[dh][k] = (bf16x8){lo[0], lo[1], lo[2], lo[3], hh[0], hh[1], hh[2], hh[3]}; }
;         bf16x8 kf[NQ][2];
; #pragma unroll
;         for (int d0 = 0; d0 < NQ; ++d0) { kf[d0][0] = *(const LAS bf16x8*)(kb + d0 * 2048); kf[d0][1] = *(const LAS bf16x8*)(kb + d0 * 2048 + 512); }
;         {
;             if (DIFF) {
; #pragma unroll
;                 for (int r = 0; r < 16; ++r) negm1[r] = -mref1;
;             }
;             f32x16 s0 = negm1, s1 = negm1;
; #pragma unroll
;             for (int d0 = 0; d0 < NQ; ++d0) {
;                 s0 = __builtin_amdgcn_mfma_f32_32x32x16_bf16(kf[d0][0], qf[d0], s0, 0, 0, 0);
;                 s1 = __builtin_amdgcn_mfma_f32_32x32x16_bf16(kf[d0][1], qf[d0], s1, 0, 0, 0);
;             }
;             softmax_pv(s0, s1, mref1, negm1, l1, o1, scr, vf, t == 0, r32, hi);
.LBB0_495:
	s_bitcmp1_b32 s34, 0
	s_cselect_b32 s18, 0xa000, 0
	v_add_u32_e32 v187, s18, v181
	v_add_u32_e32 v163, s18, v184
	ds_read_b128 v[234:237], v187
	ds_read_b128 v[238:241], v187 offset:512
	ds_read_b128 v[242:245], v187 offset:2048
	ds_read_b128 v[188:191], v187 offset:2560
	s_waitcnt lgkmcnt(0)
	v_mfma_f32_32x32x16_bf16 v[80:95], v[234:237], v[104:107], v[194:209]
	v_mfma_f32_32x32x16_bf16 v[80:95], v[242:245], v[112:115], v[80:95]
	ds_read_b64_tr_b16 v[128:129], v163 offset:12288
	ds_read_b64_tr_b16 v[130:131], v163 offset:12800
	ds_read_b64_tr_b16 v[144:145], v163 offset:16384
	ds_read_b64_tr_b16 v[146:147], v163 offset:16896
	ds_read_b64_tr_b16 v[132:133], v163 offset:13312
	ds_read_b64_tr_b16 v[134:135], v163 offset:13824
	ds_read_b64_tr_b16 v[148:149], v163 offset:17408
	ds_read_b64_tr_b16 v[150:151], v163 offset:17920
	s_nop 1
	s_cmp_eq_u32 s34, 0
	s_cbranch_scc1 .Ldr_first_00
.Ldr_cont_00:
	v_exp_f32_e32 v80, v80
	v_exp_f32_e32 v81, v81
	v_mfma_f32_32x32x16_bf16 v[64:79], v[238:241], v[104:107], v[194:209]
	v_exp_f32_e32 v82, v82
	v_exp_f32_e32 v83, v83
	v_exp_f32_e32 v84, v84
	v_mfma_f32_32x32x16_bf16 v[64:79], v[188:191], v[112:115], v[64:79]
	v_exp_f32_e32 v85, v85
	v_exp_f32_e32 v86, v86
	v_exp_f32_e32 v87, v87
	v_cvt_pk_bf16_f32 v210, v80, v81
	v_cvt_pk_bf16_f32 v211, v82, v83
	v_cvt_pk_bf16_f32 v212, v84, v85
	v_cvt_pk_bf16_f32 v213, v86, v87
	v_mfma_f32_4x4x4_16b_bf16 v[164:167], v[210:211], v[214:215], v[164:167]
.Ldr_join_00:
	ds_read_b128 v[234:237], v187 offset:4096
	ds_read_b128 v[238:241], v187 offset:4608
	ds_read_b128 v[242:245], v187 offset:6144
	ds_read_b128 v[188:191], v187 offset:6656
	s_waitcnt lgkmcnt(7)
	ds_read_b64_tr_b16 v[136:137], v163 offset:14336
	ds_read_b64_tr_b16 v[138:139], v163 offset:14848
	ds_read_b64_tr_b16 v[152:153], v163 offset:18432
	ds_read_b64_tr_b16 v[154:155], v163 offset:18944
	ds_read_b64_tr_b16 v[140:141], v163 offset:15360
	ds_read_b64_tr_b16 v[142:143], v163 offset:15872
	ds_read_b64_tr_b16 v[156:157], v163 offset:19456
	ds_read_b64_tr_b16 v[158:159], v163 offset:19968
	v_exp_f32_e32 v88, v88
	v_exp_f32_e32 v89, v89
	v_mfma_f32_4x4x4_16b_bf16 v[164:167], v[212:213], v[214:215], v[164:167]
	v_exp_f32_e32 v90, v90
	v_mfma_f32_32x32x16_bf16 v[32:47], v[210:213], v[128:131], v[32:47]
	v_exp_f32_e32 v91, v91
	v_exp_f32_e32 v92, v92
	v_mfma_f32_32x32x16_bf16 v[48:63], v[210:213], v[144:147], v[48:63]
	v_exp_f32_e32 v93, v93
	v_exp_f32_e32 v94, v94
	v_exp_f32_e32 v95, v95
	v_cvt_pk_bf16_f32 v248, v88, v89
	v_cvt_pk_bf16_f32 v249, v90, v91
	v_cvt_pk_bf16_f32 v250, v92, v93
	v_cvt_pk_bf16_f32 v251, v94, v95
	v_mfma_f32_4x4x4_16b_bf16 v[164:167], v[248:249], v[214:215], v[164:167]
	v_exp_f32_e32 v64, v64
	v_exp_f32_e32 v65, v65
	v_mfma_f32_4x4x4_16b_bf16 v[164:167], v[250:251], v[214:215], v[164:167]
	s_waitcnt lgkmcnt(12)
	v_mfma_f32_32x32x16_bf16 v[32:47], v[248:251], v[132:135], v[32:47]
	v_exp_f32_e32 v66, v66
	v_exp_f32_e32 v67, v67
	v_mfma_f32_32x32x16_bf16 v[48:63], v[248:251], v[148:151], v[48:63]
	v_exp_f32_e32 v68, v68
	v_exp_f32_e32 v69, v69
	s_waitcnt lgkmcnt(8)
	v_mfma_f32_32x32x16_bf16 v[80:95], v[234:237], v[120:123], v[218:233]
	v_exp_f32_e32 v70, v70
	v_exp_f32_e32 v71, v71
	v_cvt_pk_bf16_f32 v210, v64, v65
	v_cvt_pk_bf16_f32 v211, v66, v67
	v_cvt_pk_bf16_f32 v212, v68, v69
	v_cvt_pk_bf16_f32 v213, v70, v71
	v_mfma_f32_4x4x4_16b_bf16 v[164:167], v[210:211], v[214:215], v[164:167]
	v_exp_f32_e32 v72, v72
	v_exp_f32_e32 v73, v73
	v_mfma_f32_4x4x4_16b_bf16 v[164:167], v[212:213], v[214:215], v[164:167]
	v_mfma_f32_32x32x16_bf16 v[80:95], v[242:245], v[124:127], v[80:95]
	v_exp_f32_e32 v74, v74
	v_exp_f32_e32 v75, v75
	s_waitcnt lgkmcnt(4)
	v_mfma_f32_32x32x16_bf16 v[32:47], v[210:213], v[136:139], v[32:47]
	v_exp_f32_e32 v76, v76
	v_exp_f32_e32 v77, v77
	v_mfma_f32_32x32x16_bf16 v[48:63], v[210:213], v[152:155], v[48:63]
	v_exp_f32_e32 v78, v78
	v_exp_f32_e32 v79, v79
	v_cvt_pk_bf16_f32 v248, v72, v73
	v_cvt_pk_bf16_f32 v249, v74, v75
	v_cvt_pk_bf16_f32 v250, v76, v77
	v_cvt_pk_bf16_f32 v251, v78, v79
	v_mfma_f32_4x4x4_16b_bf16 v[164:167], v[248:249], v[214:215], v[164:167]
	s_nop 1
	v_mfma_f32_4x4x4_16b_bf16 v[164:167], v[250:251], v[214:215], v[164:167]
	s_cmp_eq_u32 s34, 0
	s_cbranch_scc1 .Ldr_first_01
.Ldr_cont_01:
	v_exp_f32_e32 v80, v80
	v_mfma_f32_32x32x16_bf16 v[64:79], v[238:241], v[120:123], v[218:233]
	v_exp_f32_e32 v81, v81
	v_mfma_f32_32x32x16_bf16 v[64:79], v[188:191], v[124:127], v[64:79]
	v_exp_f32_e32 v82, v82
	v_exp_f32_e32 v83, v83
	s_waitcnt lgkmcnt(0)
	v_mfma_f32_32x32x16_bf16 v[32:47], v[248:251], v[140:143], v[32:47]
	v_exp_f32_e32 v84, v84
	v_exp_f32_e32 v85, v85
	v_mfma_f32_32x32x16_bf16 v[48:63], v[248:251], v[156:159], v[48:63]
	v_exp_f32_e32 v86, v86
	v_exp_f32_e32 v87, v87
	v_cvt_pk_bf16_f32 v210, v80, v81
	v_cvt_pk_bf16_f32 v211, v82, v83
	v_cvt_pk_bf16_f32 v212, v84, v85
	v_cvt_pk_bf16_f32 v213, v86, v87
	v_mfma_f32_4x4x4_16b_bf16 v[172:175], v[210:211], v[214:215], v[172:175]
; #define LAS __attribute__((address_space(3)))
; __device__ __forceinline__ unsigned cvt_pk_bf16(float lo, float hi) { const f32x2 v = {lo, hi}; const bf16x2_t b = __builtin_convertvector(v, bf16x2_t); return __builtin_bit_cast(unsigned, b); }
; __device__ __forceinline__ void softmax_pv(f32x16& s0, f32x16& s1, float& mref, f32x16& negm, float& lsum, f32x16 (&o)[2], LAS float* fac, const bf16x8 (&vf)[2][4], bool first, int r32, int hi) {
;     ...
;     float ps0 = 0.f, ps1 = 0.f;
; #pragma unroll
;     for (int r = 0; r < 16; ++r) { s0[r] = __builtin_amdgcn_exp2f(s0[r]); s1[r] = __builtin_amdgcn_exp2f(s1[r]); ps0 += s0[r]; ps1 += s1[r]; }
;     lsum += ps0 + ps1;
;     bf16x8 pa[4];
; #pragma unroll
;     for (int k = 0; k < 4; ++k) {
;         const f32x16& s = (k < 2) ? s0 : s1; const int rb = 8 * (k & 1);
;         u32x4 w; w.x = cvt_pk_bf16(s[rb + 0], s[rb + 1]); w.y = cvt_pk_bf16(s[rb + 2], s[rb + 3]); w.z = cvt_pk_bf16(s[rb + 4], s[rb + 5]); w.w = cvt_pk_bf16(s[rb + 6], s[rb + 7]);
;         pa[k] = __builtin_bit_cast(bf16x8, w);
;     }
; #pragma unroll
;     for (int k = 0; k < 4; ++k) {
;         o[0] = __builtin_amdgcn_mfma_f32_32x32x16_bf16(pa[k], vf[0][k], o[0], 0, 0, 0);
;         o[1] = __builtin_amdgcn_mfma_f32_32x32x16_bf16(pa[k], vf[1][k], o[1], 0, 0, 0);
;     }
; template <bool DIFF>
; __device__ __forceinline__ void attn_item(const Params& p, int l, int I, LAS unsigned char* lds, const int tid) {
;     ...
;             bf16x8 kg[2][2];
; #pragma unroll
;             for (int d0 = 0; d0 < 2; ++d0) { kg[d0][0] = *(const LAS bf16x8*)(kb + 4096 + d0 * 2048); kg[d0][1] = *(const LAS bf16x8*)(kb + 4096 + d0 * 2048 + 512); }
; #pragma unroll
;             for (int d0 = 0; d0 < 2; ++d0) {
;                 s0 = __builtin_amdgcn_mfma_f32_32x32x16_bf16(kg[d0][0], qf[2 + d0], s0, 0, 0, 0);
;                 s1 = __builtin_amdgcn_mfma_f32_32x32x16_bf16(kg[d0][1], qf[2 + d0], s1, 0, 0, 0);
;             }
;             softmax_pv(s0, s1, mref2, negm2, l2, o2, scr + 32, vf, t == 0, r32, hi);
.Ldr_join_01:
	ds_read_b128 v[234:237], v187 offset:20480
	ds_read_b128 v[238:241], v187 offset:20992
	ds_read_b128 v[242:245], v187 offset:22528
	ds_read_b128 v[188:191], v187 offset:23040
	v_exp_f32_e32 v88, v88
	v_exp_f32_e32 v89, v89
	v_mfma_f32_4x4x4_16b_bf16 v[172:175], v[212:213], v[214:215], v[172:175]
	v_exp_f32_e32 v90, v90
	v_mfma_f32_32x32x16_bf16 v[0:15], v[210:213], v[128:131], v[0:15]
	v_exp_f32_e32 v91, v91
	v_exp_f32_e32 v92, v92
	v_mfma_f32_32x32x16_bf16 v[16:31], v[210:213], v[144:147], v[16:31]
	v_exp_f32_e32 v93, v93
	v_exp_f32_e32 v94, v94
	v_exp_f32_e32 v95, v95
	v_cvt_pk_bf16_f32 v248, v88, v89
	v_cvt_pk_bf16_f32 v249, v90, v91
	v_cvt_pk_bf16_f32 v250, v92, v93
	v_cvt_pk_bf16_f32 v251, v94, v95
	v_mfma_f32_4x4x4_16b_bf16 v[172:175], v[248:249], v[214:215], v[172:175]
	v_exp_f32_e32 v64, v64
	v_exp_f32_e32 v65, v65
	v_mfma_f32_4x4x4_16b_bf16 v[172:175], v[250:251], v[214:215], v[172:175]
	v_mfma_f32_32x32x16_bf16 v[0:15], v[248:251], v[132:135], v[0:15]
	v_exp_f32_e32 v66, v66
	v_exp_f32_e32 v67, v67
	v_mfma_f32_32x32x16_bf16 v[16:31], v[248:251], v[148:151], v[16:31]
	v_exp_f32_e32 v68, v68
	v_exp_f32_e32 v69, v69
	s_waitcnt lgkmcnt(0)
	v_mfma_f32_32x32x16_bf16 v[80:95], v[234:237], v[104:107], v[194:209]
	v_exp_f32_e32 v70, v70
	v_exp_f32_e32 v71, v71
	v_cvt_pk_bf16_f32 v210, v64, v65
	v_cvt_pk_bf16_f32 v211, v66, v67
	v_cvt_pk_bf16_f32 v212, v68, v69
	v_cvt_pk_bf16_f32 v213, v70, v71
	v_mfma_f32_4x4x4_16b_bf16 v[172:175], v[210:211], v[214:215], v[172:175]
	v_exp_f32_e32 v72, v72
	v_exp_f32_e32 v73, v73
	v_mfma_f32_4x4x4_16b_bf16 v[172:175], v[212:213], v[214:215], v[172:175]
	v_mfma_f32_32x32x16_bf16 v[80:95], v[242:245], v[112:115], v[80:95]
	v_exp_f32_e32 v74, v74
	v_exp_f32_e32 v75, v75
	v_mfma_f32_32x32x16_bf16 v[0:15], v[210:213], v[136:139], v[0:15]
	v_exp_f32_e32 v76, v76
	v_exp_f32_e32 v77, v77
	v_mfma_f32_32x32x16_bf16 v[16:31], v[210:213], v[152:155], v[16:31]
	v_exp_f32_e32 v78, v78
	v_exp_f32_e32 v79, v79
	v_cvt_pk_bf16_f32 v248, v72, v73
	v_cvt_pk_bf16_f32 v249, v74, v75
	v_cvt_pk_bf16_f32 v250, v76, v77
	v_cvt_pk_bf16_f32 v251, v78, v79
	v_mfma_f32_4x4x4_16b_bf16 v[172:175], v[248:249], v[214:215], v[172:175]
	s_nop 1
	v_mfma_f32_4x4x4_16b_bf16 v[172:175], v[250:251], v[214:215], v[172:175]
	ds_read_b64_tr_b16 v[128:129], v163 offset:32768
	ds_read_b64_tr_b16 v[130:131], v163 offset:33280
	ds_read_b64_tr_b16 v[144:145], v163 offset:36864
	ds_read_b64_tr_b16 v[146:147], v163 offset:37376
	ds_read_b64_tr_b16 v[132:133], v163 offset:33792
	ds_read_b64_tr_b16 v[134:135], v163 offset:34304
	ds_read_b64_tr_b16 v[148:149], v163 offset:37888
	ds_read_b64_tr_b16 v[150:151], v163 offset:38400
	v_exp_f32_e32 v80, v80
	v_mfma_f32_32x32x16_bf16 v[64:79], v[238:241], v[104:107], v[194:209]
	v_exp_f32_e32 v81, v81
	v_mfma_f32_32x32x16_bf16 v[64:79], v[188:191], v[112:115], v[64:79]
	v_exp_f32_e32 v82, v82
	v_exp_f32_e32 v83, v83
	v_mfma_f32_32x32x16_bf16 v[0:15], v[248:251], v[140:143], v[0:15]
	v_exp_f32_e32 v84, v84
	v_exp_f32_e32 v85, v85
	v_mfma_f32_32x32x16_bf16 v[16:31], v[248:251], v[156:159], v[16:31]
	v_exp_f32_e32 v86, v86
	v_exp_f32_e32 v87, v87
	v_cvt_pk_bf16_f32 v210, v80, v81
	v_cvt_pk_bf16_f32 v211, v82, v83
	v_cvt_pk_bf16_f32 v212, v84, v85
	v_cvt_pk_bf16_f32 v213, v86, v87
	v_mfma_f32_4x4x4_16b_bf16 v[164:167], v[210:211], v[214:215], v[164:167]
	ds_read_b128 v[234:237], v187 offset:24576
	ds_read_b128 v[238:241], v187 offset:25088
	ds_read_b128 v[242:245], v187 offset:26624
	ds_read_b128 v[188:191], v187 offset:27136
	s_waitcnt lgkmcnt(7)
	ds_read_b64_tr_b16 v[136:137], v163 offset:34816
	ds_read_b64_tr_b16 v[138:139], v163 offset:35328
	ds_read_b64_tr_b16 v[152:153], v163 offset:38912
	ds_read_b64_tr_b16 v[154:155], v163 offset:39424
	ds_read_b64_tr_b16 v[140:141], v163 offset:35840
	ds_read_b64_tr_b16 v[142:143], v163 offset:36352
	ds_read_b64_tr_b16 v[156:157], v163 offset:39936
	ds_read_b64_tr_b16 v[158:159], v163 offset:40448
	v_exp_f32_e32 v88, v88
	v_exp_f32_e32 v89, v89
	v_mfma_f32_4x4x4_16b_bf16 v[164:167], v[212:213], v[214:215], v[164:167]
	v_exp_f32_e32 v90, v90
	v_mfma_f32_32x32x16_bf16 v[32:47], v[210:213], v[128:131], v[32:47]
	v_exp_f32_e32 v91, v91
	v_exp_f32_e32 v92, v92
	v_mfma_f32_32x32x16_bf16 v[48:63], v[210:213], v[144:147], v[48:63]
	v_exp_f32_e32 v93, v93
	v_exp_f32_e32 v94, v94
	v_exp_f32_e32 v95, v95
	v_cvt_pk_bf16_f32 v248, v88, v89
	v_cvt_pk_bf16_f32 v249, v90, v91
	v_cvt_pk_bf16_f32 v250, v92, v93
	v_cvt_pk_bf16_f32 v251, v94, v95
	v_mfma_f32_4x4x4_16b_bf16 v[164:167], v[248:249], v[214:215], v[164:167]
	v_exp_f32_e32 v64, v64
	v_exp_f32_e32 v65, v65
	v_mfma_f32_4x4x4_16b_bf16 v[164:167], v[250:251], v[214:215], v[164:167]
	s_waitcnt lgkmcnt(12)
; __device__ __forceinline__ unsigned cvt_pk_bf16(float lo, float hi) { const f32x2 v = {lo, hi}; const bf16x2_t b = __builtin_convertvector(v, bf16x2_t); return __builtin_bit_cast(unsigned, b); }
; __device__ __forceinline__ int crow(int r, int hi) { return (r & 3) + 8 * (r >> 2) + 4 * hi; }
; __device__ __forceinline__ void softmax_pv(f32x16& s0, f32x16& s1, float& mref, f32x16& negm, float& lsum, f32x16 (&o)[2], LAS float* fac, const bf16x8 (&vf)[2][4], bool first, int r32, int hi) {
;     ...
;     if (__builtin_expect(first || __any(mx > 16.0f), 0)) {
;         const float d = first ? mx : fmaxf(mx, 0.f);
;         const float f = __builtin_amdgcn_exp2f(-d);
;         lsum *= f; mref += d;
; #pragma unroll
;         for (int r = 0; r < 16; ++r) { s0[r] -= d; s1[r] -= d; negm[r] = -mref; }
;         if (hi == 0) fac[r32] = f;
;         asm volatile("s_waitcnt lgkmcnt(0)" ::: "memory");
; #pragma unroll
;         for (int r = 0; r < 16; ++r) { const float ff = fac[crow(r, hi)]; o[0][r] *= ff; o[1][r] *= ff; }
;     }
;     float ps0 = 0.f, ps1 = 0.f;
; #pragma unroll
;     for (int r = 0; r < 16; ++r) { s0[r] = __builtin_amdgcn_exp2f(s0[r]); s1[r] = __builtin_amdgcn_exp2f(s1[r]); ps0 += s0[r]; ps1 += s1[r]; }
;     lsum += ps0 + ps1;
;     bf16x8 pa[4];
; #pragma unroll
;     for (int k = 0; k < 4; ++k) {
;         const f32x16& s = (k < 2) ? s0 : s1; const int rb = 8 * (k & 1);
;         u32x4 w; w.x = cvt_pk_bf16(s[rb + 0], s[rb + 1]); w.y = cvt_pk_bf16(s[rb + 2], s[rb + 3]); w.z = cvt_pk_bf16(s[rb + 4], s[rb + 5]); w.w = cvt_pk_bf16(s[rb + 6], s[rb + 7]);
;         pa[k] = __builtin_bit_cast(bf16x8, w);
;     }
; #pragma unroll
;     for (int k = 0; k < 4; ++k) {
;         o[0] = __builtin_amdgcn_mfma_f32_32x32x16_bf16(pa[k], vf[0][k], o[0], 0, 0, 0);
;         o[1] = __builtin_amdgcn_mfma_f32_32x32x16_bf16(pa[k], vf[1][k], o[1], 0, 0, 0);
;     }
	v_mfma_f32_32x32x16_bf16 v[32:47], v[248:251], v[132:135], v[32:47]
	v_exp_f32_e32 v66, v66
	v_exp_f32_e32 v67, v67
	v_mfma_f32_32x32x16_bf16 v[48:63], v[248:251], v[148:151], v[48:63]
	v_exp_f32_e32 v68, v68
	v_exp_f32_e32 v69, v69
	s_waitcnt lgkmcnt(8)
	v_mfma_f32_32x32x16_bf16 v[80:95], v[234:237], v[120:123], v[218:233]
	v_exp_f32_e32 v70, v70
	v_exp_f32_e32 v71, v71
	v_cvt_pk_bf16_f32 v210, v64, v65
	v_cvt_pk_bf16_f32 v211, v66, v67
	v_cvt_pk_bf16_f32 v212, v68, v69
	v_cvt_pk_bf16_f32 v213, v70, v71
	v_mfma_f32_4x4x4_16b_bf16 v[164:167], v[210:211], v[214:215], v[164:167]
	v_exp_f32_e32 v72, v72
	v_exp_f32_e32 v73, v73
	v_mfma_f32_4x4x4_16b_bf16 v[164:167], v[212:213], v[214:215], v[164:167]
	v_mfma_f32_32x32x16_bf16 v[80:95], v[242:245], v[124:127], v[80:95]
	v_exp_f32_e32 v74, v74
	v_exp_f32_e32 v75, v75
	s_waitcnt lgkmcnt(4)
	v_mfma_f32_32x32x16_bf16 v[32:47], v[210:213], v[136:139], v[32:47]
	v_exp_f32_e32 v76, v76
	v_exp_f32_e32 v77, v77
	v_mfma_f32_32x32x16_bf16 v[48:63], v[210:213], v[152:155], v[48:63]
	v_exp_f32_e32 v78, v78
	v_exp_f32_e32 v79, v79
	v_cvt_pk_bf16_f32 v248, v72, v73
	v_cvt_pk_bf16_f32 v249, v74, v75
	v_cvt_pk_bf16_f32 v250, v76, v77
	v_cvt_pk_bf16_f32 v251, v78, v79
	v_mfma_f32_4x4x4_16b_bf16 v[164:167], v[248:249], v[214:215], v[164:167]
	s_nop 1
	v_mfma_f32_4x4x4_16b_bf16 v[164:167], v[250:251], v[214:215], v[164:167]
	v_exp_f32_e32 v80, v80
	v_exp_f32_e32 v81, v81
	v_mfma_f32_32x32x16_bf16 v[64:79], v[238:241], v[120:123], v[218:233]
	v_exp_f32_e32 v82, v82
	v_exp_f32_e32 v83, v83
	v_mfma_f32_32x32x16_bf16 v[64:79], v[188:191], v[124:127], v[64:79]
	v_exp_f32_e32 v84, v84
	v_exp_f32_e32 v85, v85
	s_waitcnt lgkmcnt(0)
	v_mfma_f32_32x32x16_bf16 v[32:47], v[248:251], v[140:143], v[32:47]
	v_exp_f32_e32 v86, v86
	v_exp_f32_e32 v87, v87
	v_cvt_pk_bf16_f32 v210, v80, v81
	v_cvt_pk_bf16_f32 v211, v82, v83
	v_cvt_pk_bf16_f32 v212, v84, v85
	v_cvt_pk_bf16_f32 v213, v86, v87
	v_mfma_f32_4x4x4_16b_bf16 v[172:175], v[210:211], v[214:215], v[172:175]
	v_exp_f32_e32 v88, v88
	v_exp_f32_e32 v89, v89
	v_mfma_f32_4x4x4_16b_bf16 v[172:175], v[212:213], v[214:215], v[172:175]
	v_mfma_f32_32x32x16_bf16 v[48:63], v[248:251], v[156:159], v[48:63]
	v_exp_f32_e32 v90, v90
	v_exp_f32_e32 v91, v91
	v_mfma_f32_32x32x16_bf16 v[0:15], v[210:213], v[128:131], v[0:15]
	v_exp_f32_e32 v92, v92
	v_exp_f32_e32 v93, v93
	v_mfma_f32_32x32x16_bf16 v[16:31], v[210:213], v[144:147], v[16:31]
	v_exp_f32_e32 v94, v94
	v_exp_f32_e32 v95, v95
	v_cvt_pk_bf16_f32 v248, v88, v89
	v_cvt_pk_bf16_f32 v249, v90, v91
	v_cvt_pk_bf16_f32 v250, v92, v93
	v_cvt_pk_bf16_f32 v251, v94, v95
	v_mfma_f32_4x4x4_16b_bf16 v[172:175], v[248:249], v[214:215], v[172:175]
	v_exp_f32_e32 v64, v64
	v_exp_f32_e32 v65, v65
	v_mfma_f32_4x4x4_16b_bf16 v[172:175], v[250:251], v[214:215], v[172:175]
	v_exp_f32_e32 v66, v66
	v_mfma_f32_32x32x16_bf16 v[0:15], v[248:251], v[132:135], v[0:15]
	v_exp_f32_e32 v67, v67
	v_exp_f32_e32 v68, v68
	v_mfma_f32_32x32x16_bf16 v[16:31], v[248:251], v[148:151], v[16:31]
	v_exp_f32_e32 v69, v69
	v_exp_f32_e32 v70, v70
	v_exp_f32_e32 v71, v71
	v_cvt_pk_bf16_f32 v210, v64, v65
	v_cvt_pk_bf16_f32 v211, v66, v67
	v_cvt_pk_bf16_f32 v212, v68, v69
	v_cvt_pk_bf16_f32 v213, v70, v71
	v_mfma_f32_4x4x4_16b_bf16 v[172:175], v[210:211], v[214:215], v[172:175]
	v_exp_f32_e32 v72, v72
	v_exp_f32_e32 v73, v73
	v_mfma_f32_4x4x4_16b_bf16 v[172:175], v[212:213], v[214:215], v[172:175]
	v_exp_f32_e32 v74, v74
	v_mfma_f32_32x32x16_bf16 v[0:15], v[210:213], v[136:139], v[0:15]
	v_exp_f32_e32 v75, v75
	v_exp_f32_e32 v76, v76
	v_mfma_f32_32x32x16_bf16 v[16:31], v[210:213], v[152:155], v[16:31]
	v_exp_f32_e32 v77, v77
	v_exp_f32_e32 v78, v78
	v_exp_f32_e32 v79, v79
	v_cvt_pk_bf16_f32 v248, v72, v73
	v_cvt_pk_bf16_f32 v249, v74, v75
	v_cvt_pk_bf16_f32 v250, v76, v77
	v_cvt_pk_bf16_f32 v251, v78, v79
	v_mfma_f32_4x4x4_16b_bf16 v[172:175], v[248:249], v[214:215], v[172:175]
	s_nop 1
	v_mfma_f32_4x4x4_16b_bf16 v[172:175], v[250:251], v[214:215], v[172:175]
	v_mfma_f32_32x32x16_bf16 v[0:15], v[248:251], v[140:143], v[0:15]
	v_mfma_f32_32x32x16_bf16 v[16:31], v[248:251], v[156:159], v[16:31]
	s_nop 5
	v_max3_f32 v210, v164, v165, v166
	v_max3_f32 v210, v210, v167, v172
	v_max3_f32 v210, v210, v173, v174
	v_max_f32_e32 v210, v210, v175
	v_cmp_lt_f32_e32 vcc, 0x47800000, v210
	s_cbranch_vccnz .Ldq

; __device__ __forceinline__ int crow(int r, int hi) { return (r & 3) + 8 * (r >> 2) + 4 * hi; }
; __device__ __forceinline__ float half_max(float m) { auto rr = __builtin_amdgcn_permlane32_swap(__float_as_uint(m), __float_as_uint(m), false, false); return fmaxf(__uint_as_float(rr[0]), __uint_as_float(rr[1])); }
; __device__ __forceinline__ void softmax_pv(f32x16& s0, f32x16& s1, float& mref, f32x16& negm, float& lsum, f32x16 (&o)[2], LAS float* fac, const bf16x8 (&vf)[2][4], bool first, int r32, int hi) {
;     float ma = fmaxf(fmaxf(s0[0], s0[1]), s0[2]), mb = fmaxf(fmaxf(s1[0], s1[1]), s1[2]);
; #pragma unroll
;     for (int r = 3; r < 15; r += 2) { ma = fmaxf(fmaxf(ma, s0[r]), s0[r + 1]); mb = fmaxf(fmaxf(mb, s1[r]), s1[r + 1]); }
;     float mx = fmaxf(fmaxf(ma, mb), fmaxf(s0[15], s1[15]));
;     mx = half_max(mx);
;     if (__builtin_expect(first || __any(mx > 16.0f), 0)) {
;         const float d = first ? mx : fmaxf(mx, 0.f);
;         const float f = __builtin_amdgcn_exp2f(-d);
;         lsum *= f; mref += d;
; #pragma unroll
;         for (int r = 0; r < 16; ++r) { s0[r] -= d; s1[r] -= d; negm[r] = -mref; }
;         if (hi == 0) fac[r32] = f;
;         asm volatile("s_waitcnt lgkmcnt(0)" ::: "memory");
; #pragma unroll
;         for (int r = 0; r < 16; ++r) { const float ff = fac[crow(r, hi)]; o[0][r] *= ff; o[1][r] *= ff; }
.Ldr_first_00:
	s_waitcnt lgkmcnt(0)
	v_mfma_f32_32x32x16_bf16 v[64:79], v[238:241], v[104:107], v[194:209]
	v_mfma_f32_32x32x16_bf16 v[64:79], v[188:191], v[112:115], v[64:79]
	s_nop 7
	s_nop 3
	v_max3_f32 v210, v80, v81, v82
	v_max3_f32 v211, v64, v65, v66
	v_max3_f32 v210, v210, v83, v84
	v_max3_f32 v211, v211, v67, v68
	v_max3_f32 v210, v210, v85, v86
	v_max3_f32 v211, v211, v69, v70
	v_max3_f32 v210, v210, v87, v88
	v_max3_f32 v211, v211, v71, v72
	v_max3_f32 v210, v210, v89, v90
	v_max3_f32 v211, v211, v73, v74
	v_max3_f32 v210, v210, v91, v92
	v_max3_f32 v211, v211, v75, v76
	v_max3_f32 v210, v210, v93, v94
	v_max3_f32 v211, v211, v77, v78
	v_max_f32_e32 v212, v95, v79
	v_max3_f32 v210, v210, v211, v212
	v_mov_b32_e32 v211, v210
	s_nop 1
	v_permlane32_swap_b32_e32 v210, v211
	v_max_f32_e32 v160, v210, v211
	v_exp_f32_e64 v246, -v160
	v_sub_f32_e32 v80, v80, v160
	v_sub_f32_e32 v64, v64, v160
	v_sub_f32_e32 v81, v81, v160
	v_sub_f32_e32 v65, v65, v160
	v_sub_f32_e32 v82, v82, v160
	v_sub_f32_e32 v66, v66, v160
	v_sub_f32_e32 v83, v83, v160
	v_sub_f32_e32 v67, v67, v160
	v_sub_f32_e32 v84, v84, v160
	v_sub_f32_e32 v68, v68, v160
	v_sub_f32_e32 v85, v85, v160
	v_sub_f32_e32 v69, v69, v160
	v_sub_f32_e32 v86, v86, v160
	v_sub_f32_e32 v70, v70, v160
	v_sub_f32_e32 v87, v87, v160
	v_sub_f32_e32 v71, v71, v160
	v_sub_f32_e32 v88, v88, v160
	v_sub_f32_e32 v72, v72, v160
	v_sub_f32_e32 v89, v89, v160
	v_sub_f32_e32 v73, v73, v160
	v_sub_f32_e32 v90, v90, v160
	v_sub_f32_e32 v74, v74, v160
	v_sub_f32_e32 v91, v91, v160
	v_sub_f32_e32 v75, v75, v160
	v_sub_f32_e32 v92, v92, v160
	v_sub_f32_e32 v76, v76, v160
	v_sub_f32_e32 v93, v93, v160
	v_sub_f32_e32 v77, v77, v160
	v_sub_f32_e32 v94, v94, v160
	v_sub_f32_e32 v78, v78, v160
	v_sub_f32_e32 v95, v95, v160
	v_sub_f32_e32 v79, v79, v160
	s_and_saveexec_b64 s[20:21], s[4:5]
	ds_write_b32 v180, v246
	s_or_b64 exec, exec, s[20:21]
	v_add_f32_e32 v186, v186, v160
	v_xor_b32_e32 v194, 0x80000000, v186
	v_mov_b32_e32 v195, v194
	v_mov_b32_e32 v196, v194
	v_mov_b32_e32 v197, v194
	v_mov_b32_e32 v198, v194
	v_mov_b32_e32 v199, v194
	v_mov_b32_e32 v200, v194
	v_mov_b32_e32 v201, v194
	v_mov_b32_e32 v202, v194
	v_mov_b32_e32 v203, v194
	v_mov_b32_e32 v204, v194
	v_mov_b32_e32 v205, v194
	v_mov_b32_e32 v206, v194
	v_mov_b32_e32 v207, v194
	v_mov_b32_e32 v208, v194
	v_mov_b32_e32 v209, v194
	s_waitcnt lgkmcnt(0)
	v_add_u32_e32 v160, s35, v192
	ds_read_b128 v[210:213], v160
	ds_read_b128 v[248:251], v160 offset:32
	s_waitcnt lgkmcnt(0)
	v_pk_mul_f32 v[32:33], v[32:33], v[210:211]
	v_pk_mul_f32 v[34:35], v[34:35], v[212:213]
	v_pk_mul_f32 v[36:37], v[36:37], v[248:249]
	v_pk_mul_f32 v[38:39], v[38:39], v[250:251]
	v_pk_mul_f32 v[48:49], v[48:49], v[210:211]
	v_pk_mul_f32 v[50:51], v[50:51], v[212:213]
	v_pk_mul_f32 v[52:53], v[52:53], v[248:249]
	v_pk_mul_f32 v[54:55], v[54:55], v[250:251]
	ds_read_b128 v[210:213], v160 offset:64
	ds_read_b128 v[248:251], v160 offset:96
	s_waitcnt lgkmcnt(0)
	v_pk_mul_f32 v[40:41], v[40:41], v[210:211]
	v_pk_mul_f32 v[42:43], v[42:43], v[212:213]
	v_pk_mul_f32 v[44:45], v[44:45], v[248:249]
	v_pk_mul_f32 v[46:47], v[46:47], v[250:251]
	v_pk_mul_f32 v[56:57], v[56:57], v[210:211]
	v_pk_mul_f32 v[58:59], v[58:59], v[212:213]
	v_pk_mul_f32 v[60:61], v[60:61], v[248:249]
	v_pk_mul_f32 v[62:63], v[62:63], v[250:251]
	v_exp_f32_e32 v80, v80
	v_exp_f32_e32 v81, v81
	v_exp_f32_e32 v82, v82
	v_exp_f32_e32 v83, v83
	v_exp_f32_e32 v84, v84
	v_exp_f32_e32 v85, v85
	v_exp_f32_e32 v86, v86
	v_exp_f32_e32 v87, v87
	v_cvt_pk_bf16_f32 v210, v80, v81
	v_cvt_pk_bf16_f32 v211, v82, v83
	v_cvt_pk_bf16_f32 v212, v84, v85
	v_cvt_pk_bf16_f32 v213, v86, v87
	v_mfma_f32_4x4x4_16b_bf16 v[164:167], v[210:211], v[214:215], v[164:167]
	s_branch .Ldr_join_00
